# grid syncs: barrier-object pointer and group-count loads issued before the L2 write-back instead of after it
# speedup vs baseline: 1.0108x; 1.0016x over previous
; #define SEAM(k) do { if (IN(k) && IN((k) + 1)) grid.sync(); } while (0)
; __global__ void __launch_bounds__(NWAVES * 64, 2) hymba_fwd(Params P) {
;     ...
;     SEAM(0);
.LBB0_98:
	s_cmp_gt_i32 s71, 1
	s_cselect_b64 s[4:5], -1, 0
	s_and_b64 s[2:3], s[10:11], s[4:5]
	s_andn2_b64 vcc, exec, s[2:3]
	v_cmp_eq_u32_e64 s[2:3], 0, v0
	s_cbranch_vccnz .LBB0_110
	s_waitcnt lgkmcnt(0)
	s_barrier
	s_and_saveexec_b64 s[10:11], s[2:3]
	s_cbranch_execz .LBB0_109
	s_load_dwordx2 s[2:3], s[34:35], 0x58
	v_mov_b32_e32 v3, 0
	s_mov_b64 s[12:13], exec
	v_mbcnt_lo_u32_b32 v2, s12, 0
	v_mbcnt_hi_u32_b32 v2, s13, v2
	s_waitcnt lgkmcnt(0)
	global_load_dword v1, v3, s[2:3] offset:40
	buffer_wbl2 sc1
	s_waitcnt vmcnt(0)
	v_cmp_eq_u32_e32 vcc, 0, v2
	s_and_saveexec_b64 s[16:17], vcc
	s_cbranch_execz .LBB0_102
	s_bcnt1_i32_b64 s12, s[12:13]
	v_mov_b32_e32 v4, s12
	global_atomic_add v4, v3, v4, s[2:3] offset:32 sc0

; #define SEAM(k) do { if (IN(k) && IN((k) + 1)) grid.sync(); } while (0)
; __global__ void __launch_bounds__(NWAVES * 64, 2) hymba_fwd(Params P) {
;     ...
;     SEAM(1);
.LBB0_127:
	s_cmp_gt_i32 s71, 2
	s_cselect_b64 s[2:3], -1, 0
	s_and_b64 s[4:5], s[4:5], s[2:3]
	s_andn2_b64 vcc, exec, s[4:5]
	s_cbranch_vccnz .LBB0_139
	v_cmp_eq_u32_e32 vcc, 0, v0
	s_waitcnt lgkmcnt(0)
	s_barrier
	s_and_saveexec_b64 s[4:5], vcc
	s_cbranch_execz .LBB0_138
	s_load_dwordx2 s[8:9], s[34:35], 0x58
	v_mov_b32_e32 v3, 0
	s_mov_b64 s[10:11], exec
	v_mbcnt_lo_u32_b32 v2, s10, 0
	v_mbcnt_hi_u32_b32 v2, s11, v2
	s_waitcnt lgkmcnt(0)
	global_load_dword v1, v3, s[8:9] offset:40
	buffer_wbl2 sc1
	s_waitcnt vmcnt(0)
	v_cmp_eq_u32_e32 vcc, 0, v2
	s_and_saveexec_b64 s[12:13], vcc
	s_cbranch_execz .LBB0_131
	s_bcnt1_i32_b64 s10, s[10:11]
	v_mov_b32_e32 v4, s10
	global_atomic_add v4, v3, v4, s[8:9] offset:32 sc0

; #define SEAM(k) do { if (IN(k) && IN((k) + 1)) grid.sync(); } while (0)
; __global__ void __launch_bounds__(NWAVES * 64, 2) hymba_fwd(Params P) {
;     ...
;     SEAM(2);
.LBB0_148:
	s_cmp_gt_i32 s71, 3
	s_cselect_b64 s[2:3], -1, 0
	s_and_b64 s[4:5], s[24:25], s[2:3]
	s_andn2_b64 vcc, exec, s[4:5]
	s_cbranch_vccnz .LBB0_160
	v_cmp_eq_u32_e32 vcc, 0, v0
	s_waitcnt lgkmcnt(0)
	s_barrier
	s_and_saveexec_b64 s[4:5], vcc
	s_cbranch_execz .LBB0_159
	s_load_dwordx2 s[6:7], s[34:35], 0x58
	v_mov_b32_e32 v3, 0
	s_mov_b64 s[8:9], exec
	v_mbcnt_lo_u32_b32 v2, s8, 0
	v_mbcnt_hi_u32_b32 v2, s9, v2
	s_waitcnt lgkmcnt(0)
	global_load_dword v1, v3, s[6:7] offset:40
	buffer_wbl2 sc1
	s_waitcnt vmcnt(0)
	v_cmp_eq_u32_e32 vcc, 0, v2
	s_and_saveexec_b64 s[10:11], vcc
	s_cbranch_execz .LBB0_152
	s_bcnt1_i32_b64 s8, s[8:9]
	v_mov_b32_e32 v4, s8
	global_atomic_add v4, v3, v4, s[6:7] offset:32 sc0

; #define SEAM(k) do { if (IN(k) && IN((k) + 1)) grid.sync(); } while (0)
; __global__ void __launch_bounds__(NWAVES * 64, 2) hymba_fwd(Params P) {
;     ...
;     SEAM(3);
.LBB0_338:
	s_cmp_gt_u32 s71, 4
	s_cselect_b64 s[2:3], -1, 0
	s_and_b64 s[2:3], s[6:7], s[2:3]
	s_andn2_b64 vcc, exec, s[2:3]
	s_cbranch_vccnz .LBB0_350
	v_cmp_eq_u32_e32 vcc, 0, v0
	s_waitcnt lgkmcnt(0)
	s_barrier
	s_and_saveexec_b64 s[2:3], vcc
	s_cbranch_execz .LBB0_349
	s_load_dwordx2 s[4:5], s[34:35], 0x58
	v_mov_b32_e32 v3, 0
	s_mov_b64 s[6:7], exec
	v_mbcnt_lo_u32_b32 v2, s6, 0
	v_mbcnt_hi_u32_b32 v2, s7, v2
	s_waitcnt lgkmcnt(0)
	global_load_dword v1, v3, s[4:5] offset:40
	buffer_wbl2 sc1
	s_waitcnt vmcnt(0)
	v_cmp_eq_u32_e32 vcc, 0, v2
	s_and_saveexec_b64 s[8:9], vcc
	s_cbranch_execz .LBB0_342
	s_bcnt1_i32_b64 s6, s[6:7]
	v_mov_b32_e32 v4, s6
	global_atomic_add v4, v3, v4, s[4:5] offset:32 sc0

; #define SEAM(k) do { if (IN(k) && IN((k) + 1)) grid.sync(); } while (0)
; __global__ void __launch_bounds__(NWAVES * 64, 2) hymba_fwd(Params P) {
;     ...
;     SEAM(5);
.LBB0_475:
	s_cmp_gt_u32 s71, 6
	s_cselect_b64 s[2:3], -1, 0
	s_and_b64 s[2:3], s[12:13], s[2:3]
	s_andn2_b64 vcc, exec, s[2:3]
	s_cbranch_vccnz .LBB0_487
	v_cmp_eq_u32_e32 vcc, 0, v0
	s_waitcnt lgkmcnt(0)
	s_barrier
	s_and_saveexec_b64 s[2:3], vcc
	s_cbranch_execz .LBB0_486
	s_load_dwordx2 s[4:5], s[34:35], 0x58
	v_mov_b32_e32 v3, 0
	s_mov_b64 s[6:7], exec
	v_mbcnt_lo_u32_b32 v2, s6, 0
	v_mbcnt_hi_u32_b32 v2, s7, v2
	s_waitcnt lgkmcnt(0)
	global_load_dword v1, v3, s[4:5] offset:40
	buffer_wbl2 sc1
	s_waitcnt vmcnt(0)
	v_cmp_eq_u32_e32 vcc, 0, v2
	s_and_saveexec_b64 s[8:9], vcc
	s_cbranch_execz .LBB0_479
	s_bcnt1_i32_b64 s6, s[6:7]
	v_mov_b32_e32 v4, s6
	global_atomic_add v4, v3, v4, s[4:5] offset:32 sc0

; #define SEAM(k) do { if (IN(k) && IN((k) + 1)) grid.sync(); } while (0)
; __global__ void __launch_bounds__(NWAVES * 64, 2) hymba_fwd(Params P) {
;     ...
;         SEAM(6 + 2 * half);
.LBB0_504:
	s_cmp_lt_i32 s71, 8
	s_cbranch_scc1 .LBB0_516
	s_waitcnt lgkmcnt(0)
	s_barrier
	s_and_saveexec_b64 s[4:5], s[2:3]
	s_cbranch_execz .LBB0_515
	s_load_dwordx2 s[8:9], s[34:35], 0x58
	v_mov_b32_e32 v4, 0
	s_mov_b64 s[10:11], exec
	v_mbcnt_lo_u32_b32 v3, s10, 0
	v_mbcnt_hi_u32_b32 v3, s11, v3
	s_waitcnt lgkmcnt(0)
	global_load_dword v2, v4, s[8:9] offset:40
	buffer_wbl2 sc1
	s_waitcnt vmcnt(0)
	v_cmp_eq_u32_e32 vcc, 0, v3
	s_and_saveexec_b64 s[12:13], vcc
	s_cbranch_execz .LBB0_508
	s_bcnt1_i32_b64 s10, s[10:11]
	v_mov_b32_e32 v5, s10
	global_atomic_add v5, v4, v5, s[8:9] offset:32 sc0

; #define SEAM(k) do { if (IN(k) && IN((k) + 1)) grid.sync(); } while (0)
; __global__ void __launch_bounds__(NWAVES * 64, 2) hymba_fwd(Params P) {
;     ...
;         SEAM(7 + 2 * half);
.LBB0_560:
	s_waitcnt lgkmcnt(0)
	s_barrier
	s_and_saveexec_b64 s[10:11], s[2:3]
	s_cbranch_execz .LBB0_570
	s_load_dwordx2 s[12:13], s[34:35], 0x58
	v_mov_b32_e32 v4, 0
	s_mov_b64 s[24:25], exec
	v_mbcnt_lo_u32_b32 v3, s24, 0
	v_mbcnt_hi_u32_b32 v3, s25, v3
	s_waitcnt lgkmcnt(0)
	global_load_dword v2, v4, s[12:13] offset:40
	buffer_wbl2 sc1
	s_waitcnt vmcnt(0)
	v_cmp_eq_u32_e32 vcc, 0, v3
	s_and_saveexec_b64 s[26:27], vcc
	s_cbranch_execz .LBB0_563
	s_bcnt1_i32_b64 s24, s[24:25]
	v_mov_b32_e32 v5, s24
	global_atomic_add v5, v4, v5, s[12:13] offset:32 sc0

; #define SEAM(k) do { if (IN(k) && IN((k) + 1)) grid.sync(); } while (0)
; __global__ void __launch_bounds__(NWAVES * 64, 2) hymba_fwd(Params P) {
;     ...
;         SEAM(6 + 2 * half);
.LBB0_588:
	s_cmp_lt_i32 s71, 10
	s_cbranch_scc1 .LBB0_600
	s_waitcnt lgkmcnt(0)
	s_barrier
	s_and_saveexec_b64 s[6:7], s[2:3]
	s_cbranch_execz .LBB0_599
	s_load_dwordx2 s[10:11], s[34:35], 0x58
	v_mov_b32_e32 v4, 0
	s_mov_b64 s[12:13], exec
	v_mbcnt_lo_u32_b32 v3, s12, 0
	v_mbcnt_hi_u32_b32 v3, s13, v3
	s_waitcnt lgkmcnt(0)
	global_load_dword v2, v4, s[10:11] offset:40
	buffer_wbl2 sc1
	s_waitcnt vmcnt(0)
	v_cmp_eq_u32_e32 vcc, 0, v3
	s_and_saveexec_b64 s[18:19], vcc
	s_cbranch_execz .LBB0_592
	s_bcnt1_i32_b64 s12, s[12:13]
	v_mov_b32_e32 v5, s12
	global_atomic_add v5, v4, v5, s[10:11] offset:32 sc0

; #define SEAM(k) do { if (IN(k) && IN((k) + 1)) grid.sync(); } while (0)
; __global__ void __launch_bounds__(NWAVES * 64, 2) hymba_fwd(Params P) {
;     ...
;         SEAM(7 + 2 * half);
.LBB0_644:
	s_waitcnt lgkmcnt(0)
	s_barrier
	s_and_saveexec_b64 s[4:5], s[2:3]
	s_cbranch_execz .LBB0_654
	s_load_dwordx2 s[2:3], s[34:35], 0x58
	v_mov_b32_e32 v3, 0
	s_mov_b64 s[6:7], exec
	v_mbcnt_lo_u32_b32 v2, s6, 0
	v_mbcnt_hi_u32_b32 v2, s7, v2
	s_waitcnt lgkmcnt(0)
	global_load_dword v1, v3, s[2:3] offset:40
	buffer_wbl2 sc1
	s_waitcnt vmcnt(0)
	v_cmp_eq_u32_e32 vcc, 0, v2
	s_and_saveexec_b64 s[8:9], vcc
	s_cbranch_execz .LBB0_647
	s_bcnt1_i32_b64 s6, s[6:7]
	v_mov_b32_e32 v4, s6
	global_atomic_add v4, v3, v4, s[2:3] offset:32 sc0
